# P1 epilogue rewritten by hand: one kind dispatch per tile, converts read accumulators in place, SGPR store addressing (no 64-bit VALU address math, no merge copies), permlane butterflies for the Layer
# speedup vs baseline: 1.0174x; 1.0174x over previous
; #define LAS __attribute__((address_space(3)))
;     __device__ __forceinline__ void operator()(const f32x4 (&acc)[2][2][4][2], const pg8::Unit& u, int wr, int wc, int fr, int fq, const LAS float* tab) const {
;         int kind = 0, pm = u.pm, pn = u.pn, ldc = INW; bf16_t* base = O;
;         if (mode == 0) { const int seg = pn >> 2; kind = (seg == 1 || seg == 4 || seg == 6) ? 1 : (seg == 5 ? 2 : (seg == 3 ? 3 : 0)); }
;         else if (mode == 1) { ldc = 256; if (pm >= 8) { pm -= 8; } else { pm -= 4; pn -= 8; base = O2; } base += (size_t)(pm * 4 + pn) * 65536; pm = 0; pn = 0; }
;         else { ldc = DMODEL; kind = 4; }
;         int col0 = pn * 256 + wc * 32 + 8 * fq; const int row0 = pm * 256 + wr * 64 + fr;
;         if (mode == 0) { ldc = 256; base = O + (size_t)pn * NTOK * 256; col0 = wc * 32 + 8 * fq; }
; #pragma unroll
;         for (int ai = 0; ai < 2; ++ai)
; #pragma unroll
;             for (int m = 0; m < 4; ++m) {
;                 const int row = row0 + ai * 128 + m * 16;
;                 bf16_t* rowp = (mode == 0) ? base + (size_t)(row >> 4) * 4096 + (size_t)(wc * 512 + (row & 15) * 32 + 8 * fq) : base + (size_t)row * ldc + col0;
;                 const int bjstep = (mode == 0) ? 4 * 512 : 128;
;                 float s1 = 0.f, s2 = 0.f;
;                 const float f2 = (kind == 4) ? tab[512 + ai * 128 + wr * 64 + m * 16 + fr] : 1.0f;
; #pragma unroll
;                 for (int bj = 0; bj < 2; ++bj) {
;                     f32x4 v0 = acc[ai][bj][m][0], v1 = acc[ai][bj][m][1];
;                     if (kind == 1) {
; #pragma unroll
;                         for (int e = 0; e < 4; ++e) { v0[e] = silu_f(v0[e]); v1[e] = silu_f(v1[e]); }
;                     } else if (kind == 2) { v0 = v0 * QSCALE; v1 = v1 * QSCALE; }
;                     else if (kind == 3) {
; #pragma unroll
;                         for (int e = 0; e < 4; ++e) { s1 += v0[e] + v1[e]; s2 += v0[e] * v0[e] + v1[e] * v1[e]; }
;                     } else if (kind == 4) {
;                         v0 = v0 * f2; v1 = v1 * f2;
; #pragma unroll
;                         for (int e = 0; e < 4; ++e) s2 += v0[e] * v0[e] + v1[e] * v1[e];
;                     }
;                     u32x4 w; w.x = cvt_pk_bf16(v0[0], v0[1]); w.y = cvt_pk_bf16(v0[2], v0[3]); w.z = cvt_pk_bf16(v1[0], v1[1]); w.w = cvt_pk_bf16(v1[2], v1[3]);
;                     *(u32x4*)(rowp + bj * bjstep) = w;
.LBB0_199:
	v_and_b32_e32 v218, 15, v164
	v_bfe_u32 v219, v164, 4, 2
	v_lshlrev_b32_e32 v218, 6, v218
	v_lshl_or_b32 v218, v219, 4, v218
	s_and_b32 s93, s33, 3
	s_lshl_b32 s94, s93, 10
	v_or_b32_e32 v218, s94, v218
	v_and_b32_e32 v219, 15, v164
	v_lshlrev_b32_e32 v219, 7, v219
	s_lshl_b32 s94, s4, 23
	s_lshl_b32 s95, s46, 4
	s_lshr_b32 s98, s33, 2
	s_lshl_b32 s99, s98, 2
	s_add_i32 s95, s95, s99
	s_lshl_b32 s95, s95, 13
	s_add_u32 s94, s94, s95
	s_add_u32 s96, s36, s94
	s_addc_u32 s97, s37, 0
	s_lshr_b32 s94, s4, 2
	s_cmp_eq_u32 s94, 1
	s_cbranch_scc1 .Lepi_silu
	s_cmp_eq_u32 s94, 4
	s_cbranch_scc1 .Lepi_silu
	s_cmp_eq_u32 s94, 6
	s_cbranch_scc1 .Lepi_silu
	s_cmp_eq_u32 s94, 5
	s_cbranch_scc1 .Lepi_scale
	s_cmp_eq_u32 s94, 3
	s_cbranch_scc1 .Lepi_stats
.Lepi_plain:
	v_cvt_pk_bf16_f32 v232, v126, v127
	v_cvt_pk_bf16_f32 v233, v128, v129
	v_cvt_pk_bf16_f32 v234, v122, v123
	v_cvt_pk_bf16_f32 v235, v124, v125
	global_store_dwordx4 v218, v[232:235], s[96:97]
	s_add_u32 s96, s96, 0x1000
	s_addc_u32 s97, s97, 0
	v_cvt_pk_bf16_f32 v236, v118, v119
	v_cvt_pk_bf16_f32 v237, v120, v121
	v_cvt_pk_bf16_f32 v238, v114, v115
	v_cvt_pk_bf16_f32 v239, v116, v117
	global_store_dwordx4 v218, v[236:239], s[96:97]
	s_add_u32 s96, s96, 0x1000
	s_addc_u32 s97, s97, 0
	v_cvt_pk_bf16_f32 v232, v110, v111
	v_cvt_pk_bf16_f32 v233, v112, v113
	v_cvt_pk_bf16_f32 v234, v106, v107
	v_cvt_pk_bf16_f32 v235, v108, v109
	global_store_dwordx4 v218, v[232:235], s[96:97]
	s_add_u32 s96, s96, 0x1000
	s_addc_u32 s97, s97, 0
	v_cvt_pk_bf16_f32 v236, v102, v103
	v_cvt_pk_bf16_f32 v237, v104, v105
	v_cvt_pk_bf16_f32 v238, v98, v99
	v_cvt_pk_bf16_f32 v239, v100, v101
	global_store_dwordx4 v218, v[236:239], s[96:97]
	s_add_u32 s96, s96, 0x1000
	s_addc_u32 s97, s97, 0
	v_cvt_pk_bf16_f32 v232, v94, v95
	v_cvt_pk_bf16_f32 v233, v96, v97
	v_cvt_pk_bf16_f32 v234, v90, v91
	v_cvt_pk_bf16_f32 v235, v92, v93
	global_store_dwordx4 v218, v[232:235], s[96:97]
	s_add_u32 s96, s96, 0x1000
	s_addc_u32 s97, s97, 0
	v_cvt_pk_bf16_f32 v236, v86, v87
	v_cvt_pk_bf16_f32 v237, v88, v89
	v_cvt_pk_bf16_f32 v238, v82, v83
	v_cvt_pk_bf16_f32 v239, v84, v85
	global_store_dwordx4 v218, v[236:239], s[96:97]
	s_add_u32 s96, s96, 0x1000
	s_addc_u32 s97, s97, 0
	v_cvt_pk_bf16_f32 v232, v78, v79
	v_cvt_pk_bf16_f32 v233, v80, v81
	v_cvt_pk_bf16_f32 v234, v74, v75
	v_cvt_pk_bf16_f32 v235, v76, v77
	global_store_dwordx4 v218, v[232:235], s[96:97]
	s_add_u32 s96, s96, 0x1000
	s_addc_u32 s97, s97, 0
	v_cvt_pk_bf16_f32 v236, v70, v71
	v_cvt_pk_bf16_f32 v237, v72, v73
	v_cvt_pk_bf16_f32 v238, v66, v67
	v_cvt_pk_bf16_f32 v239, v68, v69
	global_store_dwordx4 v218, v[236:239], s[96:97]
	s_add_u32 s96, s96, 0x1000
	s_addc_u32 s97, s97, 0
	s_add_u32 s96, s96, 0x8000
	s_addc_u32 s97, s97, 0
	v_cvt_pk_bf16_f32 v232, v62, v63
	v_cvt_pk_bf16_f32 v233, v64, v65
	v_cvt_pk_bf16_f32 v234, v58, v59
	v_cvt_pk_bf16_f32 v235, v60, v61
	global_store_dwordx4 v218, v[232:235], s[96:97]
	s_add_u32 s96, s96, 0x1000
	s_addc_u32 s97, s97, 0
	v_cvt_pk_bf16_f32 v236, v54, v55
	v_cvt_pk_bf16_f32 v237, v56, v57
	v_cvt_pk_bf16_f32 v238, v50, v51
	v_cvt_pk_bf16_f32 v239, v52, v53
	global_store_dwordx4 v218, v[236:239], s[96:97]
	s_add_u32 s96, s96, 0x1000
	s_addc_u32 s97, s97, 0
	v_cvt_pk_bf16_f32 v232, v46, v47
	v_cvt_pk_bf16_f32 v233, v48, v49
	v_cvt_pk_bf16_f32 v234, v42, v43
	v_cvt_pk_bf16_f32 v235, v44, v45
	global_store_dwordx4 v218, v[232:235], s[96:97]
	s_add_u32 s96, s96, 0x1000
	s_addc_u32 s97, s97, 0
	v_cvt_pk_bf16_f32 v236, v38, v39
	v_cvt_pk_bf16_f32 v237, v40, v41
	v_cvt_pk_bf16_f32 v238, v34, v35
	v_cvt_pk_bf16_f32 v239, v36, v37
	global_store_dwordx4 v218, v[236:239], s[96:97]
	s_add_u32 s96, s96, 0x1000
	s_addc_u32 s97, s97, 0
	v_cvt_pk_bf16_f32 v232, v30, v31
	v_cvt_pk_bf16_f32 v233, v32, v33
	v_cvt_pk_bf16_f32 v234, v26, v27
	v_cvt_pk_bf16_f32 v235, v28, v29
	global_store_dwordx4 v218, v[232:235], s[96:97]
	s_add_u32 s96, s96, 0x1000
	s_addc_u32 s97, s97, 0
	v_cvt_pk_bf16_f32 v236, v22, v23
	v_cvt_pk_bf16_f32 v237, v24, v25
	v_cvt_pk_bf16_f32 v238, v18, v19
	v_cvt_pk_bf16_f32 v239, v20, v21
	global_store_dwordx4 v218, v[236:239], s[96:97]
	s_add_u32 s96, s96, 0x1000
	s_addc_u32 s97, s97, 0
	v_cvt_pk_bf16_f32 v232, v14, v15
	v_cvt_pk_bf16_f32 v233, v16, v17
	v_cvt_pk_bf16_f32 v234, v10, v11
	v_cvt_pk_bf16_f32 v235, v12, v13
	global_store_dwordx4 v218, v[232:235], s[96:97]
	s_add_u32 s96, s96, 0x1000
	s_addc_u32 s97, s97, 0
	v_cvt_pk_bf16_f32 v236, v6, v7
	v_cvt_pk_bf16_f32 v237, v8, v9
	v_cvt_pk_bf16_f32 v238, v2, v3
	v_cvt_pk_bf16_f32 v239, v4, v5
	global_store_dwordx4 v218, v[236:239], s[96:97]
	s_add_u32 s96, s96, 0x1000
	s_addc_u32 s97, s97, 0
	s_branch .LBB0_391
; __device__ __forceinline__ unsigned cvt_pk_bf16(float lo, float hi) { unsigned r; asm volatile("v_cvt_pk_bf16_f32 %0, %1, %2" : "=v"(r) : "v"(lo), "v"(hi)); return r; }
; __device__ __forceinline__ float silu_f(float x) { return x * __builtin_amdgcn_rcpf(1.0f + __builtin_amdgcn_exp2f(-x * LOG2E)); }
;     __device__ __forceinline__ void operator()(const f32x4 (&acc)[2][2][4][2], const pg8::Unit& u, int wr, int wc, int fr, int fq, const LAS float* tab) const {
;     ...
;                     if (kind == 1) {
; #pragma unroll
;                         for (int e = 0; e < 4; ++e) { v0[e] = silu_f(v0[e]); v1[e] = silu_f(v1[e]); }
;                     } else if (kind == 2) { v0 = v0 * QSCALE; v1 = v1 * QSCALE; }
;                     else if (kind == 3) {
; #pragma unroll
;                         for (int e = 0; e < 4; ++e) { s1 += v0[e] + v1[e]; s2 += v0[e] * v0[e] + v1[e] * v1[e]; }
;                     } else if (kind == 4) {
;                         v0 = v0 * f2; v1 = v1 * f2;
; #pragma unroll
;                         for (int e = 0; e < 4; ++e) s2 += v0[e] * v0[e] + v1[e] * v1[e];
;                     }
;                     u32x4 w; w.x = cvt_pk_bf16(v0[0], v0[1]); w.y = cvt_pk_bf16(v0[2], v0[3]); w.z = cvt_pk_bf16(v1[0], v1[1]); w.w = cvt_pk_bf16(v1[2], v1[3]);
;                     *(u32x4*)(rowp + bj * bjstep) = w;
.Lepi_silu:
	v_mov_b32_e32 v220, 0xbfb8aa3b
	v_mov_b32_e32 v221, 0xbfb8aa3b
	v_mov_b32_e32 v222, 1.0
	v_mov_b32_e32 v223, 1.0
	v_pk_mul_f32 v[224:225], v[126:127], v[220:221]
	v_pk_mul_f32 v[226:227], v[128:129], v[220:221]
	v_pk_mul_f32 v[228:229], v[122:123], v[220:221]
	v_pk_mul_f32 v[230:231], v[124:125], v[220:221]
	v_exp_f32_e32 v224, v224
	v_exp_f32_e32 v225, v225
	v_exp_f32_e32 v226, v226
	v_exp_f32_e32 v227, v227
	v_exp_f32_e32 v228, v228
	v_exp_f32_e32 v229, v229
	v_exp_f32_e32 v230, v230
	v_exp_f32_e32 v231, v231
	v_pk_add_f32 v[224:225], v[224:225], v[222:223]
	v_pk_add_f32 v[226:227], v[226:227], v[222:223]
	v_pk_add_f32 v[228:229], v[228:229], v[222:223]
	v_pk_add_f32 v[230:231], v[230:231], v[222:223]
	v_rcp_f32_e32 v224, v224
	v_rcp_f32_e32 v225, v225
	v_rcp_f32_e32 v226, v226
	v_rcp_f32_e32 v227, v227
	v_rcp_f32_e32 v228, v228
	v_rcp_f32_e32 v229, v229
	v_rcp_f32_e32 v230, v230
	v_rcp_f32_e32 v231, v231
	v_pk_mul_f32 v[126:127], v[126:127], v[224:225]
	v_pk_mul_f32 v[128:129], v[128:129], v[226:227]
	v_pk_mul_f32 v[122:123], v[122:123], v[228:229]
	v_pk_mul_f32 v[124:125], v[124:125], v[230:231]
	v_cvt_pk_bf16_f32 v232, v126, v127
	v_cvt_pk_bf16_f32 v233, v128, v129
	v_cvt_pk_bf16_f32 v234, v122, v123
	v_cvt_pk_bf16_f32 v235, v124, v125
	global_store_dwordx4 v218, v[232:235], s[96:97]
	s_add_u32 s96, s96, 0x1000
	s_addc_u32 s97, s97, 0
	v_pk_mul_f32 v[224:225], v[118:119], v[220:221]
	v_pk_mul_f32 v[226:227], v[120:121], v[220:221]
	v_pk_mul_f32 v[228:229], v[114:115], v[220:221]
	v_pk_mul_f32 v[230:231], v[116:117], v[220:221]
	v_exp_f32_e32 v224, v224
	v_exp_f32_e32 v225, v225
	v_exp_f32_e32 v226, v226
	v_exp_f32_e32 v227, v227
	v_exp_f32_e32 v228, v228
	v_exp_f32_e32 v229, v229
	v_exp_f32_e32 v230, v230
	v_exp_f32_e32 v231, v231
	v_pk_add_f32 v[224:225], v[224:225], v[222:223]
	v_pk_add_f32 v[226:227], v[226:227], v[222:223]
	v_pk_add_f32 v[228:229], v[228:229], v[222:223]
	v_pk_add_f32 v[230:231], v[230:231], v[222:223]
	v_rcp_f32_e32 v224, v224
	v_rcp_f32_e32 v225, v225
	v_rcp_f32_e32 v226, v226
	v_rcp_f32_e32 v227, v227
	v_rcp_f32_e32 v228, v228
	v_rcp_f32_e32 v229, v229
	v_rcp_f32_e32 v230, v230
	v_rcp_f32_e32 v231, v231
	v_pk_mul_f32 v[118:119], v[118:119], v[224:225]
	v_pk_mul_f32 v[120:121], v[120:121], v[226:227]
	v_pk_mul_f32 v[114:115], v[114:115], v[228:229]
	v_pk_mul_f32 v[116:117], v[116:117], v[230:231]
	v_cvt_pk_bf16_f32 v236, v118, v119
	v_cvt_pk_bf16_f32 v237, v120, v121
	v_cvt_pk_bf16_f32 v238, v114, v115
	v_cvt_pk_bf16_f32 v239, v116, v117
	global_store_dwordx4 v218, v[236:239], s[96:97]
	s_add_u32 s96, s96, 0x1000
	s_addc_u32 s97, s97, 0
	v_pk_mul_f32 v[224:225], v[110:111], v[220:221]
	v_pk_mul_f32 v[226:227], v[112:113], v[220:221]
	v_pk_mul_f32 v[228:229], v[106:107], v[220:221]
	v_pk_mul_f32 v[230:231], v[108:109], v[220:221]
	v_exp_f32_e32 v224, v224
	v_exp_f32_e32 v225, v225
	v_exp_f32_e32 v226, v226
	v_exp_f32_e32 v227, v227
	v_exp_f32_e32 v228, v228
	v_exp_f32_e32 v229, v229
	v_exp_f32_e32 v230, v230
	v_exp_f32_e32 v231, v231
	v_pk_add_f32 v[224:225], v[224:225], v[222:223]
	v_pk_add_f32 v[226:227], v[226:227], v[222:223]
	v_pk_add_f32 v[228:229], v[228:229], v[222:223]
	v_pk_add_f32 v[230:231], v[230:231], v[222:223]
	v_rcp_f32_e32 v224, v224
	v_rcp_f32_e32 v225, v225
	v_rcp_f32_e32 v226, v226
	v_rcp_f32_e32 v227, v227
	v_rcp_f32_e32 v228, v228
	v_rcp_f32_e32 v229, v229
	v_rcp_f32_e32 v230, v230
	v_rcp_f32_e32 v231, v231
	v_pk_mul_f32 v[110:111], v[110:111], v[224:225]
	v_pk_mul_f32 v[112:113], v[112:113], v[226:227]
	v_pk_mul_f32 v[106:107], v[106:107], v[228:229]
	v_pk_mul_f32 v[108:109], v[108:109], v[230:231]
	v_cvt_pk_bf16_f32 v232, v110, v111
	v_cvt_pk_bf16_f32 v233, v112, v113
	v_cvt_pk_bf16_f32 v234, v106, v107
	v_cvt_pk_bf16_f32 v235, v108, v109
	global_store_dwordx4 v218, v[232:235], s[96:97]
	s_add_u32 s96, s96, 0x1000
	s_addc_u32 s97, s97, 0
	v_pk_mul_f32 v[224:225], v[102:103], v[220:221]
	v_pk_mul_f32 v[226:227], v[104:105], v[220:221]
	v_pk_mul_f32 v[228:229], v[98:99], v[220:221]
	v_pk_mul_f32 v[230:231], v[100:101], v[220:221]
	v_exp_f32_e32 v224, v224
	v_exp_f32_e32 v225, v225
	v_exp_f32_e32 v226, v226
	v_exp_f32_e32 v227, v227
	v_exp_f32_e32 v228, v228
	v_exp_f32_e32 v229, v229
	v_exp_f32_e32 v230, v230
	v_exp_f32_e32 v231, v231
	v_pk_add_f32 v[224:225], v[224:225], v[222:223]
	v_pk_add_f32 v[226:227], v[226:227], v[222:223]
	v_pk_add_f32 v[228:229], v[228:229], v[222:223]
	v_pk_add_f32 v[230:231], v[230:231], v[222:223]
	v_rcp_f32_e32 v224, v224
	v_rcp_f32_e32 v225, v225
	v_rcp_f32_e32 v226, v226
	v_rcp_f32_e32 v227, v227
	v_rcp_f32_e32 v228, v228
	v_rcp_f32_e32 v229, v229
	v_rcp_f32_e32 v230, v230
	v_rcp_f32_e32 v231, v231
	v_pk_mul_f32 v[102:103], v[102:103], v[224:225]
	v_pk_mul_f32 v[104:105], v[104:105], v[226:227]
	v_pk_mul_f32 v[98:99], v[98:99], v[228:229]
	v_pk_mul_f32 v[100:101], v[100:101], v[230:231]
	v_cvt_pk_bf16_f32 v236, v102, v103
	v_cvt_pk_bf16_f32 v237, v104, v105
	v_cvt_pk_bf16_f32 v238, v98, v99
	v_cvt_pk_bf16_f32 v239, v100, v101
	global_store_dwordx4 v218, v[236:239], s[96:97]
	s_add_u32 s96, s96, 0x1000
	s_addc_u32 s97, s97, 0
	v_pk_mul_f32 v[224:225], v[94:95], v[220:221]
	v_pk_mul_f32 v[226:227], v[96:97], v[220:221]
	v_pk_mul_f32 v[228:229], v[90:91], v[220:221]
	v_pk_mul_f32 v[230:231], v[92:93], v[220:221]
	v_exp_f32_e32 v224, v224
	v_exp_f32_e32 v225, v225
	v_exp_f32_e32 v226, v226
	v_exp_f32_e32 v227, v227
	v_exp_f32_e32 v228, v228
	v_exp_f32_e32 v229, v229
	v_exp_f32_e32 v230, v230
	v_exp_f32_e32 v231, v231
	v_pk_add_f32 v[224:225], v[224:225], v[222:223]
	v_pk_add_f32 v[226:227], v[226:227], v[222:223]
	v_pk_add_f32 v[228:229], v[228:229], v[222:223]
; __device__ __forceinline__ unsigned cvt_pk_bf16(float lo, float hi) { unsigned r; asm volatile("v_cvt_pk_bf16_f32 %0, %1, %2" : "=v"(r) : "v"(lo), "v"(hi)); return r; }
; __device__ __forceinline__ float silu_f(float x) { return x * __builtin_amdgcn_rcpf(1.0f + __builtin_amdgcn_exp2f(-x * LOG2E)); }
;     __device__ __forceinline__ void operator()(const f32x4 (&acc)[2][2][4][2], const pg8::Unit& u, int wr, int wc, int fr, int fq, const LAS float* tab) const {
;     ...
;                     if (kind == 1) {
; #pragma unroll
;                         for (int e = 0; e < 4; ++e) { v0[e] = silu_f(v0[e]); v1[e] = silu_f(v1[e]); }
;                     } else if (kind == 2) { v0 = v0 * QSCALE; v1 = v1 * QSCALE; }
;                     else if (kind == 3) {
; #pragma unroll
;                         for (int e = 0; e < 4; ++e) { s1 += v0[e] + v1[e]; s2 += v0[e] * v0[e] + v1[e] * v1[e]; }
;                     } else if (kind == 4) {
;                         v0 = v0 * f2; v1 = v1 * f2;
; #pragma unroll
;                         for (int e = 0; e < 4; ++e) s2 += v0[e] * v0[e] + v1[e] * v1[e];
;                     }
;                     u32x4 w; w.x = cvt_pk_bf16(v0[0], v0[1]); w.y = cvt_pk_bf16(v0[2], v0[3]); w.z = cvt_pk_bf16(v1[0], v1[1]); w.w = cvt_pk_bf16(v1[2], v1[3]);
;                     *(u32x4*)(rowp + bj * bjstep) = w;
	v_pk_add_f32 v[230:231], v[230:231], v[222:223]
	v_rcp_f32_e32 v224, v224
	v_rcp_f32_e32 v225, v225
	v_rcp_f32_e32 v226, v226
	v_rcp_f32_e32 v227, v227
	v_rcp_f32_e32 v228, v228
	v_rcp_f32_e32 v229, v229
	v_rcp_f32_e32 v230, v230
	v_rcp_f32_e32 v231, v231
	v_pk_mul_f32 v[94:95], v[94:95], v[224:225]
	v_pk_mul_f32 v[96:97], v[96:97], v[226:227]
	v_pk_mul_f32 v[90:91], v[90:91], v[228:229]
	v_pk_mul_f32 v[92:93], v[92:93], v[230:231]
	v_cvt_pk_bf16_f32 v232, v94, v95
	v_cvt_pk_bf16_f32 v233, v96, v97
	v_cvt_pk_bf16_f32 v234, v90, v91
	v_cvt_pk_bf16_f32 v235, v92, v93
	global_store_dwordx4 v218, v[232:235], s[96:97]
	s_add_u32 s96, s96, 0x1000
	s_addc_u32 s97, s97, 0
	v_pk_mul_f32 v[224:225], v[86:87], v[220:221]
	v_pk_mul_f32 v[226:227], v[88:89], v[220:221]
	v_pk_mul_f32 v[228:229], v[82:83], v[220:221]
	v_pk_mul_f32 v[230:231], v[84:85], v[220:221]
	v_exp_f32_e32 v224, v224
	v_exp_f32_e32 v225, v225
	v_exp_f32_e32 v226, v226
	v_exp_f32_e32 v227, v227
	v_exp_f32_e32 v228, v228
	v_exp_f32_e32 v229, v229
	v_exp_f32_e32 v230, v230
	v_exp_f32_e32 v231, v231
	v_pk_add_f32 v[224:225], v[224:225], v[222:223]
	v_pk_add_f32 v[226:227], v[226:227], v[222:223]
	v_pk_add_f32 v[228:229], v[228:229], v[222:223]
	v_pk_add_f32 v[230:231], v[230:231], v[222:223]
	v_rcp_f32_e32 v224, v224
	v_rcp_f32_e32 v225, v225
	v_rcp_f32_e32 v226, v226
	v_rcp_f32_e32 v227, v227
	v_rcp_f32_e32 v228, v228
	v_rcp_f32_e32 v229, v229
	v_rcp_f32_e32 v230, v230
	v_rcp_f32_e32 v231, v231
	v_pk_mul_f32 v[86:87], v[86:87], v[224:225]
	v_pk_mul_f32 v[88:89], v[88:89], v[226:227]
	v_pk_mul_f32 v[82:83], v[82:83], v[228:229]
	v_pk_mul_f32 v[84:85], v[84:85], v[230:231]
	v_cvt_pk_bf16_f32 v236, v86, v87
	v_cvt_pk_bf16_f32 v237, v88, v89
	v_cvt_pk_bf16_f32 v238, v82, v83
	v_cvt_pk_bf16_f32 v239, v84, v85
	global_store_dwordx4 v218, v[236:239], s[96:97]
	s_add_u32 s96, s96, 0x1000
	s_addc_u32 s97, s97, 0
	v_pk_mul_f32 v[224:225], v[78:79], v[220:221]
	v_pk_mul_f32 v[226:227], v[80:81], v[220:221]
	v_pk_mul_f32 v[228:229], v[74:75], v[220:221]
	v_pk_mul_f32 v[230:231], v[76:77], v[220:221]
	v_exp_f32_e32 v224, v224
	v_exp_f32_e32 v225, v225
	v_exp_f32_e32 v226, v226
	v_exp_f32_e32 v227, v227
	v_exp_f32_e32 v228, v228
	v_exp_f32_e32 v229, v229
	v_exp_f32_e32 v230, v230
	v_exp_f32_e32 v231, v231
	v_pk_add_f32 v[224:225], v[224:225], v[222:223]
	v_pk_add_f32 v[226:227], v[226:227], v[222:223]
	v_pk_add_f32 v[228:229], v[228:229], v[222:223]
	v_pk_add_f32 v[230:231], v[230:231], v[222:223]
	v_rcp_f32_e32 v224, v224
	v_rcp_f32_e32 v225, v225
	v_rcp_f32_e32 v226, v226
	v_rcp_f32_e32 v227, v227
	v_rcp_f32_e32 v228, v228
	v_rcp_f32_e32 v229, v229
	v_rcp_f32_e32 v230, v230
	v_rcp_f32_e32 v231, v231
	v_pk_mul_f32 v[78:79], v[78:79], v[224:225]
	v_pk_mul_f32 v[80:81], v[80:81], v[226:227]
	v_pk_mul_f32 v[74:75], v[74:75], v[228:229]
	v_pk_mul_f32 v[76:77], v[76:77], v[230:231]
	v_cvt_pk_bf16_f32 v232, v78, v79
	v_cvt_pk_bf16_f32 v233, v80, v81
	v_cvt_pk_bf16_f32 v234, v74, v75
	v_cvt_pk_bf16_f32 v235, v76, v77
	global_store_dwordx4 v218, v[232:235], s[96:97]
	s_add_u32 s96, s96, 0x1000
	s_addc_u32 s97, s97, 0
	v_pk_mul_f32 v[224:225], v[70:71], v[220:221]
	v_pk_mul_f32 v[226:227], v[72:73], v[220:221]
	v_pk_mul_f32 v[228:229], v[66:67], v[220:221]
	v_pk_mul_f32 v[230:231], v[68:69], v[220:221]
	v_exp_f32_e32 v224, v224
	v_exp_f32_e32 v225, v225
	v_exp_f32_e32 v226, v226
	v_exp_f32_e32 v227, v227
	v_exp_f32_e32 v228, v228
	v_exp_f32_e32 v229, v229
	v_exp_f32_e32 v230, v230
	v_exp_f32_e32 v231, v231
	v_pk_add_f32 v[224:225], v[224:225], v[222:223]
	v_pk_add_f32 v[226:227], v[226:227], v[222:223]
	v_pk_add_f32 v[228:229], v[228:229], v[222:223]
	v_pk_add_f32 v[230:231], v[230:231], v[222:223]
	v_rcp_f32_e32 v224, v224
	v_rcp_f32_e32 v225, v225
	v_rcp_f32_e32 v226, v226
	v_rcp_f32_e32 v227, v227
	v_rcp_f32_e32 v228, v228
	v_rcp_f32_e32 v229, v229
	v_rcp_f32_e32 v230, v230
	v_rcp_f32_e32 v231, v231
	v_pk_mul_f32 v[70:71], v[70:71], v[224:225]
	v_pk_mul_f32 v[72:73], v[72:73], v[226:227]
	v_pk_mul_f32 v[66:67], v[66:67], v[228:229]
	v_pk_mul_f32 v[68:69], v[68:69], v[230:231]
	v_cvt_pk_bf16_f32 v236, v70, v71
	v_cvt_pk_bf16_f32 v237, v72, v73
	v_cvt_pk_bf16_f32 v238, v66, v67
	v_cvt_pk_bf16_f32 v239, v68, v69
	global_store_dwordx4 v218, v[236:239], s[96:97]
	s_add_u32 s96, s96, 0x1000
	s_addc_u32 s97, s97, 0
	s_add_u32 s96, s96, 0x8000
	s_addc_u32 s97, s97, 0
	v_pk_mul_f32 v[224:225], v[62:63], v[220:221]
	v_pk_mul_f32 v[226:227], v[64:65], v[220:221]
	v_pk_mul_f32 v[228:229], v[58:59], v[220:221]
	v_pk_mul_f32 v[230:231], v[60:61], v[220:221]
	v_exp_f32_e32 v224, v224
	v_exp_f32_e32 v225, v225
	v_exp_f32_e32 v226, v226
	v_exp_f32_e32 v227, v227
	v_exp_f32_e32 v228, v228
	v_exp_f32_e32 v229, v229
	v_exp_f32_e32 v230, v230
	v_exp_f32_e32 v231, v231
	v_pk_add_f32 v[224:225], v[224:225], v[222:223]
	v_pk_add_f32 v[226:227], v[226:227], v[222:223]
	v_pk_add_f32 v[228:229], v[228:229], v[222:223]
	v_pk_add_f32 v[230:231], v[230:231], v[222:223]
	v_rcp_f32_e32 v224, v224
	v_rcp_f32_e32 v225, v225
	v_rcp_f32_e32 v226, v226
	v_rcp_f32_e32 v227, v227
	v_rcp_f32_e32 v228, v228
	v_rcp_f32_e32 v229, v229
	v_rcp_f32_e32 v230, v230
	v_rcp_f32_e32 v231, v231
	v_pk_mul_f32 v[62:63], v[62:63], v[224:225]
	v_pk_mul_f32 v[64:65], v[64:65], v[226:227]
	v_pk_mul_f32 v[58:59], v[58:59], v[228:229]
	v_pk_mul_f32 v[60:61], v[60:61], v[230:231]
	v_cvt_pk_bf16_f32 v232, v62, v63
	v_cvt_pk_bf16_f32 v233, v64, v65
	v_cvt_pk_bf16_f32 v234, v58, v59
	v_cvt_pk_bf16_f32 v235, v60, v61
	global_store_dwordx4 v218, v[232:235], s[96:97]
	s_add_u32 s96, s96, 0x1000
	s_addc_u32 s97, s97, 0
	v_pk_mul_f32 v[224:225], v[54:55], v[220:221]
; __device__ __forceinline__ unsigned cvt_pk_bf16(float lo, float hi) { unsigned r; asm volatile("v_cvt_pk_bf16_f32 %0, %1, %2" : "=v"(r) : "v"(lo), "v"(hi)); return r; }
; __device__ __forceinline__ float silu_f(float x) { return x * __builtin_amdgcn_rcpf(1.0f + __builtin_amdgcn_exp2f(-x * LOG2E)); }
;     __device__ __forceinline__ void operator()(const f32x4 (&acc)[2][2][4][2], const pg8::Unit& u, int wr, int wc, int fr, int fq, const LAS float* tab) const {
;     ...
;                     if (kind == 1) {
; #pragma unroll
;                         for (int e = 0; e < 4; ++e) { v0[e] = silu_f(v0[e]); v1[e] = silu_f(v1[e]); }
;                     } else if (kind == 2) { v0 = v0 * QSCALE; v1 = v1 * QSCALE; }
;                     else if (kind == 3) {
; #pragma unroll
;                         for (int e = 0; e < 4; ++e) { s1 += v0[e] + v1[e]; s2 += v0[e] * v0[e] + v1[e] * v1[e]; }
;                     } else if (kind == 4) {
;                         v0 = v0 * f2; v1 = v1 * f2;
; #pragma unroll
;                         for (int e = 0; e < 4; ++e) s2 += v0[e] * v0[e] + v1[e] * v1[e];
;                     }
;                     u32x4 w; w.x = cvt_pk_bf16(v0[0], v0[1]); w.y = cvt_pk_bf16(v0[2], v0[3]); w.z = cvt_pk_bf16(v1[0], v1[1]); w.w = cvt_pk_bf16(v1[2], v1[3]);
;                     *(u32x4*)(rowp + bj * bjstep) = w;
	v_pk_mul_f32 v[226:227], v[56:57], v[220:221]
	v_pk_mul_f32 v[228:229], v[50:51], v[220:221]
	v_pk_mul_f32 v[230:231], v[52:53], v[220:221]
	v_exp_f32_e32 v224, v224
	v_exp_f32_e32 v225, v225
	v_exp_f32_e32 v226, v226
	v_exp_f32_e32 v227, v227
	v_exp_f32_e32 v228, v228
	v_exp_f32_e32 v229, v229
	v_exp_f32_e32 v230, v230
	v_exp_f32_e32 v231, v231
	v_pk_add_f32 v[224:225], v[224:225], v[222:223]
	v_pk_add_f32 v[226:227], v[226:227], v[222:223]
	v_pk_add_f32 v[228:229], v[228:229], v[222:223]
	v_pk_add_f32 v[230:231], v[230:231], v[222:223]
	v_rcp_f32_e32 v224, v224
	v_rcp_f32_e32 v225, v225
	v_rcp_f32_e32 v226, v226
	v_rcp_f32_e32 v227, v227
	v_rcp_f32_e32 v228, v228
	v_rcp_f32_e32 v229, v229
	v_rcp_f32_e32 v230, v230
	v_rcp_f32_e32 v231, v231
	v_pk_mul_f32 v[54:55], v[54:55], v[224:225]
	v_pk_mul_f32 v[56:57], v[56:57], v[226:227]
	v_pk_mul_f32 v[50:51], v[50:51], v[228:229]
	v_pk_mul_f32 v[52:53], v[52:53], v[230:231]
	v_cvt_pk_bf16_f32 v236, v54, v55
	v_cvt_pk_bf16_f32 v237, v56, v57
	v_cvt_pk_bf16_f32 v238, v50, v51
	v_cvt_pk_bf16_f32 v239, v52, v53
	global_store_dwordx4 v218, v[236:239], s[96:97]
	s_add_u32 s96, s96, 0x1000
	s_addc_u32 s97, s97, 0
	v_pk_mul_f32 v[224:225], v[46:47], v[220:221]
	v_pk_mul_f32 v[226:227], v[48:49], v[220:221]
	v_pk_mul_f32 v[228:229], v[42:43], v[220:221]
	v_pk_mul_f32 v[230:231], v[44:45], v[220:221]
	v_exp_f32_e32 v224, v224
	v_exp_f32_e32 v225, v225
	v_exp_f32_e32 v226, v226
	v_exp_f32_e32 v227, v227
	v_exp_f32_e32 v228, v228
	v_exp_f32_e32 v229, v229
	v_exp_f32_e32 v230, v230
	v_exp_f32_e32 v231, v231
	v_pk_add_f32 v[224:225], v[224:225], v[222:223]
	v_pk_add_f32 v[226:227], v[226:227], v[222:223]
	v_pk_add_f32 v[228:229], v[228:229], v[222:223]
	v_pk_add_f32 v[230:231], v[230:231], v[222:223]
	v_rcp_f32_e32 v224, v224
	v_rcp_f32_e32 v225, v225
	v_rcp_f32_e32 v226, v226
	v_rcp_f32_e32 v227, v227
	v_rcp_f32_e32 v228, v228
	v_rcp_f32_e32 v229, v229
	v_rcp_f32_e32 v230, v230
	v_rcp_f32_e32 v231, v231
	v_pk_mul_f32 v[46:47], v[46:47], v[224:225]
	v_pk_mul_f32 v[48:49], v[48:49], v[226:227]
	v_pk_mul_f32 v[42:43], v[42:43], v[228:229]
	v_pk_mul_f32 v[44:45], v[44:45], v[230:231]
	v_cvt_pk_bf16_f32 v232, v46, v47
	v_cvt_pk_bf16_f32 v233, v48, v49
	v_cvt_pk_bf16_f32 v234, v42, v43
	v_cvt_pk_bf16_f32 v235, v44, v45
	global_store_dwordx4 v218, v[232:235], s[96:97]
	s_add_u32 s96, s96, 0x1000
	s_addc_u32 s97, s97, 0
	v_pk_mul_f32 v[224:225], v[38:39], v[220:221]
	v_pk_mul_f32 v[226:227], v[40:41], v[220:221]
	v_pk_mul_f32 v[228:229], v[34:35], v[220:221]
	v_pk_mul_f32 v[230:231], v[36:37], v[220:221]
	v_exp_f32_e32 v224, v224
	v_exp_f32_e32 v225, v225
	v_exp_f32_e32 v226, v226
	v_exp_f32_e32 v227, v227
	v_exp_f32_e32 v228, v228
	v_exp_f32_e32 v229, v229
	v_exp_f32_e32 v230, v230
	v_exp_f32_e32 v231, v231
	v_pk_add_f32 v[224:225], v[224:225], v[222:223]
	v_pk_add_f32 v[226:227], v[226:227], v[222:223]
	v_pk_add_f32 v[228:229], v[228:229], v[222:223]
	v_pk_add_f32 v[230:231], v[230:231], v[222:223]
	v_rcp_f32_e32 v224, v224
	v_rcp_f32_e32 v225, v225
	v_rcp_f32_e32 v226, v226
	v_rcp_f32_e32 v227, v227
	v_rcp_f32_e32 v228, v228
	v_rcp_f32_e32 v229, v229
	v_rcp_f32_e32 v230, v230
	v_rcp_f32_e32 v231, v231
	v_pk_mul_f32 v[38:39], v[38:39], v[224:225]
	v_pk_mul_f32 v[40:41], v[40:41], v[226:227]
	v_pk_mul_f32 v[34:35], v[34:35], v[228:229]
	v_pk_mul_f32 v[36:37], v[36:37], v[230:231]
	v_cvt_pk_bf16_f32 v236, v38, v39
	v_cvt_pk_bf16_f32 v237, v40, v41
	v_cvt_pk_bf16_f32 v238, v34, v35
	v_cvt_pk_bf16_f32 v239, v36, v37
	global_store_dwordx4 v218, v[236:239], s[96:97]
	s_add_u32 s96, s96, 0x1000
	s_addc_u32 s97, s97, 0
	v_pk_mul_f32 v[224:225], v[30:31], v[220:221]
	v_pk_mul_f32 v[226:227], v[32:33], v[220:221]
	v_pk_mul_f32 v[228:229], v[26:27], v[220:221]
	v_pk_mul_f32 v[230:231], v[28:29], v[220:221]
	v_exp_f32_e32 v224, v224
	v_exp_f32_e32 v225, v225
	v_exp_f32_e32 v226, v226
	v_exp_f32_e32 v227, v227
	v_exp_f32_e32 v228, v228
	v_exp_f32_e32 v229, v229
	v_exp_f32_e32 v230, v230
	v_exp_f32_e32 v231, v231
	v_pk_add_f32 v[224:225], v[224:225], v[222:223]
	v_pk_add_f32 v[226:227], v[226:227], v[222:223]
	v_pk_add_f32 v[228:229], v[228:229], v[222:223]
	v_pk_add_f32 v[230:231], v[230:231], v[222:223]
	v_rcp_f32_e32 v224, v224
	v_rcp_f32_e32 v225, v225
	v_rcp_f32_e32 v226, v226
	v_rcp_f32_e32 v227, v227
	v_rcp_f32_e32 v228, v228
	v_rcp_f32_e32 v229, v229
	v_rcp_f32_e32 v230, v230
	v_rcp_f32_e32 v231, v231
	v_pk_mul_f32 v[30:31], v[30:31], v[224:225]
	v_pk_mul_f32 v[32:33], v[32:33], v[226:227]
	v_pk_mul_f32 v[26:27], v[26:27], v[228:229]
	v_pk_mul_f32 v[28:29], v[28:29], v[230:231]
	v_cvt_pk_bf16_f32 v232, v30, v31
	v_cvt_pk_bf16_f32 v233, v32, v33
	v_cvt_pk_bf16_f32 v234, v26, v27
	v_cvt_pk_bf16_f32 v235, v28, v29
	global_store_dwordx4 v218, v[232:235], s[96:97]
	s_add_u32 s96, s96, 0x1000
	s_addc_u32 s97, s97, 0
	v_pk_mul_f32 v[224:225], v[22:23], v[220:221]
	v_pk_mul_f32 v[226:227], v[24:25], v[220:221]
	v_pk_mul_f32 v[228:229], v[18:19], v[220:221]
	v_pk_mul_f32 v[230:231], v[20:21], v[220:221]
	v_exp_f32_e32 v224, v224
	v_exp_f32_e32 v225, v225
	v_exp_f32_e32 v226, v226
	v_exp_f32_e32 v227, v227
	v_exp_f32_e32 v228, v228
	v_exp_f32_e32 v229, v229
	v_exp_f32_e32 v230, v230
	v_exp_f32_e32 v231, v231
	v_pk_add_f32 v[224:225], v[224:225], v[222:223]
	v_pk_add_f32 v[226:227], v[226:227], v[222:223]
	v_pk_add_f32 v[228:229], v[228:229], v[222:223]
	v_pk_add_f32 v[230:231], v[230:231], v[222:223]
	v_rcp_f32_e32 v224, v224
	v_rcp_f32_e32 v225, v225
	v_rcp_f32_e32 v226, v226
	v_rcp_f32_e32 v227, v227
	v_rcp_f32_e32 v228, v228
	v_rcp_f32_e32 v229, v229
	v_rcp_f32_e32 v230, v230
	v_rcp_f32_e32 v231, v231
; __device__ __forceinline__ unsigned cvt_pk_bf16(float lo, float hi) { unsigned r; asm volatile("v_cvt_pk_bf16_f32 %0, %1, %2" : "=v"(r) : "v"(lo), "v"(hi)); return r; }
; __device__ __forceinline__ float silu_f(float x) { return x * __builtin_amdgcn_rcpf(1.0f + __builtin_amdgcn_exp2f(-x * LOG2E)); }
;     __device__ __forceinline__ void operator()(const f32x4 (&acc)[2][2][4][2], const pg8::Unit& u, int wr, int wc, int fr, int fq, const LAS float* tab) const {
;     ...
;                     if (kind == 1) {
; #pragma unroll
;                         for (int e = 0; e < 4; ++e) { v0[e] = silu_f(v0[e]); v1[e] = silu_f(v1[e]); }
;                     } else if (kind == 2) { v0 = v0 * QSCALE; v1 = v1 * QSCALE; }
;                     else if (kind == 3) {
; #pragma unroll
;                         for (int e = 0; e < 4; ++e) { s1 += v0[e] + v1[e]; s2 += v0[e] * v0[e] + v1[e] * v1[e]; }
;                     } else if (kind == 4) {
;                         v0 = v0 * f2; v1 = v1 * f2;
; #pragma unroll
;                         for (int e = 0; e < 4; ++e) s2 += v0[e] * v0[e] + v1[e] * v1[e];
;                     }
;                     u32x4 w; w.x = cvt_pk_bf16(v0[0], v0[1]); w.y = cvt_pk_bf16(v0[2], v0[3]); w.z = cvt_pk_bf16(v1[0], v1[1]); w.w = cvt_pk_bf16(v1[2], v1[3]);
;                     *(u32x4*)(rowp + bj * bjstep) = w;
	v_pk_mul_f32 v[22:23], v[22:23], v[224:225]
	v_pk_mul_f32 v[24:25], v[24:25], v[226:227]
	v_pk_mul_f32 v[18:19], v[18:19], v[228:229]
	v_pk_mul_f32 v[20:21], v[20:21], v[230:231]
	v_cvt_pk_bf16_f32 v236, v22, v23
	v_cvt_pk_bf16_f32 v237, v24, v25
	v_cvt_pk_bf16_f32 v238, v18, v19
	v_cvt_pk_bf16_f32 v239, v20, v21
	global_store_dwordx4 v218, v[236:239], s[96:97]
	s_add_u32 s96, s96, 0x1000
	s_addc_u32 s97, s97, 0
	v_pk_mul_f32 v[224:225], v[14:15], v[220:221]
	v_pk_mul_f32 v[226:227], v[16:17], v[220:221]
	v_pk_mul_f32 v[228:229], v[10:11], v[220:221]
	v_pk_mul_f32 v[230:231], v[12:13], v[220:221]
	v_exp_f32_e32 v224, v224
	v_exp_f32_e32 v225, v225
	v_exp_f32_e32 v226, v226
	v_exp_f32_e32 v227, v227
	v_exp_f32_e32 v228, v228
	v_exp_f32_e32 v229, v229
	v_exp_f32_e32 v230, v230
	v_exp_f32_e32 v231, v231
	v_pk_add_f32 v[224:225], v[224:225], v[222:223]
	v_pk_add_f32 v[226:227], v[226:227], v[222:223]
	v_pk_add_f32 v[228:229], v[228:229], v[222:223]
	v_pk_add_f32 v[230:231], v[230:231], v[222:223]
	v_rcp_f32_e32 v224, v224
	v_rcp_f32_e32 v225, v225
	v_rcp_f32_e32 v226, v226
	v_rcp_f32_e32 v227, v227
	v_rcp_f32_e32 v228, v228
	v_rcp_f32_e32 v229, v229
	v_rcp_f32_e32 v230, v230
	v_rcp_f32_e32 v231, v231
	v_pk_mul_f32 v[14:15], v[14:15], v[224:225]
	v_pk_mul_f32 v[16:17], v[16:17], v[226:227]
	v_pk_mul_f32 v[10:11], v[10:11], v[228:229]
	v_pk_mul_f32 v[12:13], v[12:13], v[230:231]
	v_cvt_pk_bf16_f32 v232, v14, v15
	v_cvt_pk_bf16_f32 v233, v16, v17
	v_cvt_pk_bf16_f32 v234, v10, v11
	v_cvt_pk_bf16_f32 v235, v12, v13
	global_store_dwordx4 v218, v[232:235], s[96:97]
	s_add_u32 s96, s96, 0x1000
	s_addc_u32 s97, s97, 0
	v_pk_mul_f32 v[224:225], v[6:7], v[220:221]
	v_pk_mul_f32 v[226:227], v[8:9], v[220:221]
	v_pk_mul_f32 v[228:229], v[2:3], v[220:221]
	v_pk_mul_f32 v[230:231], v[4:5], v[220:221]
	v_exp_f32_e32 v224, v224
	v_exp_f32_e32 v225, v225
	v_exp_f32_e32 v226, v226
	v_exp_f32_e32 v227, v227
	v_exp_f32_e32 v228, v228
	v_exp_f32_e32 v229, v229
	v_exp_f32_e32 v230, v230
	v_exp_f32_e32 v231, v231
	v_pk_add_f32 v[224:225], v[224:225], v[222:223]
	v_pk_add_f32 v[226:227], v[226:227], v[222:223]
	v_pk_add_f32 v[228:229], v[228:229], v[222:223]
	v_pk_add_f32 v[230:231], v[230:231], v[222:223]
	v_rcp_f32_e32 v224, v224
	v_rcp_f32_e32 v225, v225
	v_rcp_f32_e32 v226, v226
	v_rcp_f32_e32 v227, v227
	v_rcp_f32_e32 v228, v228
	v_rcp_f32_e32 v229, v229
	v_rcp_f32_e32 v230, v230
	v_rcp_f32_e32 v231, v231
	v_pk_mul_f32 v[6:7], v[6:7], v[224:225]
	v_pk_mul_f32 v[8:9], v[8:9], v[226:227]
	v_pk_mul_f32 v[2:3], v[2:3], v[228:229]
	v_pk_mul_f32 v[4:5], v[4:5], v[230:231]
	v_cvt_pk_bf16_f32 v236, v6, v7
	v_cvt_pk_bf16_f32 v237, v8, v9
	v_cvt_pk_bf16_f32 v238, v2, v3
	v_cvt_pk_bf16_f32 v239, v4, v5
	global_store_dwordx4 v218, v[236:239], s[96:97]
	s_add_u32 s96, s96, 0x1000
	s_addc_u32 s97, s97, 0
	s_branch .LBB0_391
.Lepi_scale:
	v_pk_mul_f32 v[126:127], v[126:127], s[14:15] op_sel_hi:[1,0]
	v_pk_mul_f32 v[128:129], v[128:129], s[14:15] op_sel_hi:[1,0]
	v_pk_mul_f32 v[122:123], v[122:123], s[14:15] op_sel_hi:[1,0]
	v_pk_mul_f32 v[124:125], v[124:125], s[14:15] op_sel_hi:[1,0]
	v_cvt_pk_bf16_f32 v232, v126, v127
	v_cvt_pk_bf16_f32 v233, v128, v129
	v_cvt_pk_bf16_f32 v234, v122, v123
	v_cvt_pk_bf16_f32 v235, v124, v125
	global_store_dwordx4 v218, v[232:235], s[96:97]
	s_add_u32 s96, s96, 0x1000
	s_addc_u32 s97, s97, 0
	v_pk_mul_f32 v[118:119], v[118:119], s[14:15] op_sel_hi:[1,0]
	v_pk_mul_f32 v[120:121], v[120:121], s[14:15] op_sel_hi:[1,0]
	v_pk_mul_f32 v[114:115], v[114:115], s[14:15] op_sel_hi:[1,0]
	v_pk_mul_f32 v[116:117], v[116:117], s[14:15] op_sel_hi:[1,0]
	v_cvt_pk_bf16_f32 v236, v118, v119
	v_cvt_pk_bf16_f32 v237, v120, v121
	v_cvt_pk_bf16_f32 v238, v114, v115
	v_cvt_pk_bf16_f32 v239, v116, v117
	global_store_dwordx4 v218, v[236:239], s[96:97]
	s_add_u32 s96, s96, 0x1000
	s_addc_u32 s97, s97, 0
	v_pk_mul_f32 v[110:111], v[110:111], s[14:15] op_sel_hi:[1,0]
	v_pk_mul_f32 v[112:113], v[112:113], s[14:15] op_sel_hi:[1,0]
	v_pk_mul_f32 v[106:107], v[106:107], s[14:15] op_sel_hi:[1,0]
	v_pk_mul_f32 v[108:109], v[108:109], s[14:15] op_sel_hi:[1,0]
	v_cvt_pk_bf16_f32 v232, v110, v111
	v_cvt_pk_bf16_f32 v233, v112, v113
	v_cvt_pk_bf16_f32 v234, v106, v107
	v_cvt_pk_bf16_f32 v235, v108, v109
	global_store_dwordx4 v218, v[232:235], s[96:97]
	s_add_u32 s96, s96, 0x1000
	s_addc_u32 s97, s97, 0
	v_pk_mul_f32 v[102:103], v[102:103], s[14:15] op_sel_hi:[1,0]
	v_pk_mul_f32 v[104:105], v[104:105], s[14:15] op_sel_hi:[1,0]
	v_pk_mul_f32 v[98:99], v[98:99], s[14:15] op_sel_hi:[1,0]
	v_pk_mul_f32 v[100:101], v[100:101], s[14:15] op_sel_hi:[1,0]
	v_cvt_pk_bf16_f32 v236, v102, v103
	v_cvt_pk_bf16_f32 v237, v104, v105
	v_cvt_pk_bf16_f32 v238, v98, v99
	v_cvt_pk_bf16_f32 v239, v100, v101
	global_store_dwordx4 v218, v[236:239], s[96:97]
	s_add_u32 s96, s96, 0x1000
	s_addc_u32 s97, s97, 0
	v_pk_mul_f32 v[94:95], v[94:95], s[14:15] op_sel_hi:[1,0]
	v_pk_mul_f32 v[96:97], v[96:97], s[14:15] op_sel_hi:[1,0]
	v_pk_mul_f32 v[90:91], v[90:91], s[14:15] op_sel_hi:[1,0]
	v_pk_mul_f32 v[92:93], v[92:93], s[14:15] op_sel_hi:[1,0]
	v_cvt_pk_bf16_f32 v232, v94, v95
	v_cvt_pk_bf16_f32 v233, v96, v97
	v_cvt_pk_bf16_f32 v234, v90, v91
	v_cvt_pk_bf16_f32 v235, v92, v93
	global_store_dwordx4 v218, v[232:235], s[96:97]
	s_add_u32 s96, s96, 0x1000
	s_addc_u32 s97, s97, 0
	v_pk_mul_f32 v[86:87], v[86:87], s[14:15] op_sel_hi:[1,0]
	v_pk_mul_f32 v[88:89], v[88:89], s[14:15] op_sel_hi:[1,0]
	v_pk_mul_f32 v[82:83], v[82:83], s[14:15] op_sel_hi:[1,0]
	v_pk_mul_f32 v[84:85], v[84:85], s[14:15] op_sel_hi:[1,0]
	v_cvt_pk_bf16_f32 v236, v86, v87
	v_cvt_pk_bf16_f32 v237, v88, v89
	v_cvt_pk_bf16_f32 v238, v82, v83
; __device__ __forceinline__ unsigned cvt_pk_bf16(float lo, float hi) { unsigned r; asm volatile("v_cvt_pk_bf16_f32 %0, %1, %2" : "=v"(r) : "v"(lo), "v"(hi)); return r; }
;     __device__ __forceinline__ void operator()(const f32x4 (&acc)[2][2][4][2], const pg8::Unit& u, int wr, int wc, int fr, int fq, const LAS float* tab) const {
;     ...
;                     } else if (kind == 2) { v0 = v0 * QSCALE; v1 = v1 * QSCALE; }
;     ...
;                     u32x4 w; w.x = cvt_pk_bf16(v0[0], v0[1]); w.y = cvt_pk_bf16(v0[2], v0[3]); w.z = cvt_pk_bf16(v1[0], v1[1]); w.w = cvt_pk_bf16(v1[2], v1[3]);
;                     *(u32x4*)(rowp + bj * bjstep) = w;
	v_cvt_pk_bf16_f32 v239, v84, v85
	global_store_dwordx4 v218, v[236:239], s[96:97]
	s_add_u32 s96, s96, 0x1000
	s_addc_u32 s97, s97, 0
	v_pk_mul_f32 v[78:79], v[78:79], s[14:15] op_sel_hi:[1,0]
	v_pk_mul_f32 v[80:81], v[80:81], s[14:15] op_sel_hi:[1,0]
	v_pk_mul_f32 v[74:75], v[74:75], s[14:15] op_sel_hi:[1,0]
	v_pk_mul_f32 v[76:77], v[76:77], s[14:15] op_sel_hi:[1,0]
	v_cvt_pk_bf16_f32 v232, v78, v79
	v_cvt_pk_bf16_f32 v233, v80, v81
	v_cvt_pk_bf16_f32 v234, v74, v75
	v_cvt_pk_bf16_f32 v235, v76, v77
	global_store_dwordx4 v218, v[232:235], s[96:97]
	s_add_u32 s96, s96, 0x1000
	s_addc_u32 s97, s97, 0
	v_pk_mul_f32 v[70:71], v[70:71], s[14:15] op_sel_hi:[1,0]
	v_pk_mul_f32 v[72:73], v[72:73], s[14:15] op_sel_hi:[1,0]
	v_pk_mul_f32 v[66:67], v[66:67], s[14:15] op_sel_hi:[1,0]
	v_pk_mul_f32 v[68:69], v[68:69], s[14:15] op_sel_hi:[1,0]
	v_cvt_pk_bf16_f32 v236, v70, v71
	v_cvt_pk_bf16_f32 v237, v72, v73
	v_cvt_pk_bf16_f32 v238, v66, v67
	v_cvt_pk_bf16_f32 v239, v68, v69
	global_store_dwordx4 v218, v[236:239], s[96:97]
	s_add_u32 s96, s96, 0x1000
	s_addc_u32 s97, s97, 0
	s_add_u32 s96, s96, 0x8000
	s_addc_u32 s97, s97, 0
	v_pk_mul_f32 v[62:63], v[62:63], s[14:15] op_sel_hi:[1,0]
	v_pk_mul_f32 v[64:65], v[64:65], s[14:15] op_sel_hi:[1,0]
	v_pk_mul_f32 v[58:59], v[58:59], s[14:15] op_sel_hi:[1,0]
	v_pk_mul_f32 v[60:61], v[60:61], s[14:15] op_sel_hi:[1,0]
	v_cvt_pk_bf16_f32 v232, v62, v63
	v_cvt_pk_bf16_f32 v233, v64, v65
	v_cvt_pk_bf16_f32 v234, v58, v59
	v_cvt_pk_bf16_f32 v235, v60, v61
	global_store_dwordx4 v218, v[232:235], s[96:97]
	s_add_u32 s96, s96, 0x1000
	s_addc_u32 s97, s97, 0
	v_pk_mul_f32 v[54:55], v[54:55], s[14:15] op_sel_hi:[1,0]
	v_pk_mul_f32 v[56:57], v[56:57], s[14:15] op_sel_hi:[1,0]
	v_pk_mul_f32 v[50:51], v[50:51], s[14:15] op_sel_hi:[1,0]
	v_pk_mul_f32 v[52:53], v[52:53], s[14:15] op_sel_hi:[1,0]
	v_cvt_pk_bf16_f32 v236, v54, v55
	v_cvt_pk_bf16_f32 v237, v56, v57
	v_cvt_pk_bf16_f32 v238, v50, v51
	v_cvt_pk_bf16_f32 v239, v52, v53
	global_store_dwordx4 v218, v[236:239], s[96:97]
	s_add_u32 s96, s96, 0x1000
	s_addc_u32 s97, s97, 0
	v_pk_mul_f32 v[46:47], v[46:47], s[14:15] op_sel_hi:[1,0]
	v_pk_mul_f32 v[48:49], v[48:49], s[14:15] op_sel_hi:[1,0]
	v_pk_mul_f32 v[42:43], v[42:43], s[14:15] op_sel_hi:[1,0]
	v_pk_mul_f32 v[44:45], v[44:45], s[14:15] op_sel_hi:[1,0]
	v_cvt_pk_bf16_f32 v232, v46, v47
	v_cvt_pk_bf16_f32 v233, v48, v49
	v_cvt_pk_bf16_f32 v234, v42, v43
	v_cvt_pk_bf16_f32 v235, v44, v45
	global_store_dwordx4 v218, v[232:235], s[96:97]
	s_add_u32 s96, s96, 0x1000
	s_addc_u32 s97, s97, 0
	v_pk_mul_f32 v[38:39], v[38:39], s[14:15] op_sel_hi:[1,0]
	v_pk_mul_f32 v[40:41], v[40:41], s[14:15] op_sel_hi:[1,0]
	v_pk_mul_f32 v[34:35], v[34:35], s[14:15] op_sel_hi:[1,0]
	v_pk_mul_f32 v[36:37], v[36:37], s[14:15] op_sel_hi:[1,0]
	v_cvt_pk_bf16_f32 v236, v38, v39
	v_cvt_pk_bf16_f32 v237, v40, v41
	v_cvt_pk_bf16_f32 v238, v34, v35
	v_cvt_pk_bf16_f32 v239, v36, v37
	global_store_dwordx4 v218, v[236:239], s[96:97]
	s_add_u32 s96, s96, 0x1000
	s_addc_u32 s97, s97, 0
	v_pk_mul_f32 v[30:31], v[30:31], s[14:15] op_sel_hi:[1,0]
	v_pk_mul_f32 v[32:33], v[32:33], s[14:15] op_sel_hi:[1,0]
	v_pk_mul_f32 v[26:27], v[26:27], s[14:15] op_sel_hi:[1,0]
	v_pk_mul_f32 v[28:29], v[28:29], s[14:15] op_sel_hi:[1,0]
	v_cvt_pk_bf16_f32 v232, v30, v31
	v_cvt_pk_bf16_f32 v233, v32, v33
	v_cvt_pk_bf16_f32 v234, v26, v27
	v_cvt_pk_bf16_f32 v235, v28, v29
	global_store_dwordx4 v218, v[232:235], s[96:97]
	s_add_u32 s96, s96, 0x1000
	s_addc_u32 s97, s97, 0
	v_pk_mul_f32 v[22:23], v[22:23], s[14:15] op_sel_hi:[1,0]
	v_pk_mul_f32 v[24:25], v[24:25], s[14:15] op_sel_hi:[1,0]
	v_pk_mul_f32 v[18:19], v[18:19], s[14:15] op_sel_hi:[1,0]
	v_pk_mul_f32 v[20:21], v[20:21], s[14:15] op_sel_hi:[1,0]
	v_cvt_pk_bf16_f32 v236, v22, v23
	v_cvt_pk_bf16_f32 v237, v24, v25
	v_cvt_pk_bf16_f32 v238, v18, v19
	v_cvt_pk_bf16_f32 v239, v20, v21
	global_store_dwordx4 v218, v[236:239], s[96:97]
	s_add_u32 s96, s96, 0x1000
	s_addc_u32 s97, s97, 0
	v_pk_mul_f32 v[14:15], v[14:15], s[14:15] op_sel_hi:[1,0]
	v_pk_mul_f32 v[16:17], v[16:17], s[14:15] op_sel_hi:[1,0]
	v_pk_mul_f32 v[10:11], v[10:11], s[14:15] op_sel_hi:[1,0]
	v_pk_mul_f32 v[12:13], v[12:13], s[14:15] op_sel_hi:[1,0]
	v_cvt_pk_bf16_f32 v232, v14, v15
	v_cvt_pk_bf16_f32 v233, v16, v17
	v_cvt_pk_bf16_f32 v234, v10, v11
	v_cvt_pk_bf16_f32 v235, v12, v13
	global_store_dwordx4 v218, v[232:235], s[96:97]
	s_add_u32 s96, s96, 0x1000
	s_addc_u32 s97, s97, 0
	v_pk_mul_f32 v[6:7], v[6:7], s[14:15] op_sel_hi:[1,0]
	v_pk_mul_f32 v[8:9], v[8:9], s[14:15] op_sel_hi:[1,0]
	v_pk_mul_f32 v[2:3], v[2:3], s[14:15] op_sel_hi:[1,0]
	v_pk_mul_f32 v[4:5], v[4:5], s[14:15] op_sel_hi:[1,0]
	v_cvt_pk_bf16_f32 v236, v6, v7
	v_cvt_pk_bf16_f32 v237, v8, v9
	v_cvt_pk_bf16_f32 v238, v2, v3
	v_cvt_pk_bf16_f32 v239, v4, v5
	global_store_dwordx4 v218, v[236:239], s[96:97]
	s_add_u32 s96, s96, 0x1000
	s_addc_u32 s97, s97, 0
	s_branch .LBB0_391
; __device__ __forceinline__ unsigned cvt_pk_bf16(float lo, float hi) { unsigned r; asm volatile("v_cvt_pk_bf16_f32 %0, %1, %2" : "=v"(r) : "v"(lo), "v"(hi)); return r; }
;     __device__ __forceinline__ void operator()(const f32x4 (&acc)[2][2][4][2], const pg8::Unit& u, int wr, int wc, int fr, int fq, const LAS float* tab) const {
;     ...
;                     else if (kind == 3) {
; #pragma unroll
;                         for (int e = 0; e < 4; ++e) { s1 += v0[e] + v1[e]; s2 += v0[e] * v0[e] + v1[e] * v1[e]; }
;                     } else if (kind == 4) {
;                         v0 = v0 * f2; v1 = v1 * f2;
; #pragma unroll
;                         for (int e = 0; e < 4; ++e) s2 += v0[e] * v0[e] + v1[e] * v1[e];
;                     }
;                     u32x4 w; w.x = cvt_pk_bf16(v0[0], v0[1]); w.y = cvt_pk_bf16(v0[2], v0[3]); w.z = cvt_pk_bf16(v1[0], v1[1]); w.w = cvt_pk_bf16(v1[2], v1[3]);
;                     *(u32x4*)(rowp + bj * bjstep) = w;
;                 }
;                 if (kind == 3) {
;                     s1 += __shfl_xor(s1, 16); s1 += __shfl_xor(s1, 32); s2 += __shfl_xor(s2, 16); s2 += __shfl_xor(s2, 32);
;                     if (fq == 0) { float* p = aux + (size_t)row * 32 + ((pn - 12) * 4 + wc) * 2; p[0] = s1; p[1] = s2; }
.Lepi_stats:
	s_lshl_b32 s94, s46, 8
	s_lshr_b32 s95, s33, 2
	s_lshl_b32 s95, s95, 6
	s_add_i32 s94, s94, s95
	s_lshl_b32 s94, s94, 7
	s_sub_i32 s95, s4, 12
	s_lshl_b32 s95, s95, 2
	s_add_i32 s95, s95, s93
	s_lshl_b32 s95, s95, 3
	s_add_u32 s94, s94, s95
	s_add_u32 s98, s54, s94
	s_addc_u32 s99, s55, 0
	v_mov_b32_e32 v240, v126
	v_mov_b32_e32 v241, v127
	v_pk_mul_f32 v[242:243], v[126:127], v[126:127]
	v_pk_add_f32 v[240:241], v[240:241], v[128:129]
	v_pk_fma_f32 v[242:243], v[128:129], v[128:129], v[242:243]
	v_pk_add_f32 v[240:241], v[240:241], v[122:123]
	v_pk_fma_f32 v[242:243], v[122:123], v[122:123], v[242:243]
	v_pk_add_f32 v[240:241], v[240:241], v[124:125]
	v_pk_fma_f32 v[242:243], v[124:125], v[124:125], v[242:243]
	v_pk_add_f32 v[240:241], v[240:241], v[118:119]
	v_pk_fma_f32 v[242:243], v[118:119], v[118:119], v[242:243]
	v_pk_add_f32 v[240:241], v[240:241], v[120:121]
	v_pk_fma_f32 v[242:243], v[120:121], v[120:121], v[242:243]
	v_pk_add_f32 v[240:241], v[240:241], v[114:115]
	v_pk_fma_f32 v[242:243], v[114:115], v[114:115], v[242:243]
	v_pk_add_f32 v[240:241], v[240:241], v[116:117]
	v_pk_fma_f32 v[242:243], v[116:117], v[116:117], v[242:243]
	v_add_f32_e32 v240, v240, v241
	v_add_f32_e32 v241, v242, v243
	v_mov_b32_e32 v242, v240
	v_mov_b32_e32 v243, v241
	s_nop 1
	v_permlane16_swap_b32_e32 v242, v240
	v_permlane16_swap_b32_e32 v243, v241
	v_pk_add_f32 v[240:241], v[240:241], v[242:243]
	v_mov_b32_e32 v242, v240
	v_mov_b32_e32 v243, v241
	s_nop 1
	v_permlane32_swap_b32_e32 v242, v240
	v_permlane32_swap_b32_e32 v243, v241
	v_pk_add_f32 v[244:245], v[240:241], v[242:243]
	v_cvt_pk_bf16_f32 v232, v126, v127
	v_cvt_pk_bf16_f32 v233, v128, v129
	v_cvt_pk_bf16_f32 v234, v122, v123
	v_cvt_pk_bf16_f32 v235, v124, v125
	global_store_dwordx4 v218, v[232:235], s[96:97]
	s_add_u32 s96, s96, 0x1000
	s_addc_u32 s97, s97, 0
	v_cvt_pk_bf16_f32 v236, v118, v119
	v_cvt_pk_bf16_f32 v237, v120, v121
	v_cvt_pk_bf16_f32 v238, v114, v115
	v_cvt_pk_bf16_f32 v239, v116, v117
	global_store_dwordx4 v218, v[236:239], s[96:97]
	s_add_u32 s96, s96, 0x1000
	s_addc_u32 s97, s97, 0
	s_and_saveexec_b64 vcc, s[0:1]
	global_store_dwordx2 v219, v[244:245], s[98:99]
	s_or_b64 exec, exec, vcc
	s_add_u32 s98, s98, 0x800
	s_addc_u32 s99, s99, 0
	v_mov_b32_e32 v240, v110
	v_mov_b32_e32 v241, v111
	v_pk_mul_f32 v[242:243], v[110:111], v[110:111]
	v_pk_add_f32 v[240:241], v[240:241], v[112:113]
	v_pk_fma_f32 v[242:243], v[112:113], v[112:113], v[242:243]
	v_pk_add_f32 v[240:241], v[240:241], v[106:107]
	v_pk_fma_f32 v[242:243], v[106:107], v[106:107], v[242:243]
	v_pk_add_f32 v[240:241], v[240:241], v[108:109]
	v_pk_fma_f32 v[242:243], v[108:109], v[108:109], v[242:243]
	v_pk_add_f32 v[240:241], v[240:241], v[102:103]
	v_pk_fma_f32 v[242:243], v[102:103], v[102:103], v[242:243]
	v_pk_add_f32 v[240:241], v[240:241], v[104:105]
	v_pk_fma_f32 v[242:243], v[104:105], v[104:105], v[242:243]
	v_pk_add_f32 v[240:241], v[240:241], v[98:99]
	v_pk_fma_f32 v[242:243], v[98:99], v[98:99], v[242:243]
	v_pk_add_f32 v[240:241], v[240:241], v[100:101]
	v_pk_fma_f32 v[242:243], v[100:101], v[100:101], v[242:243]
	v_add_f32_e32 v240, v240, v241
	v_add_f32_e32 v241, v242, v243
	v_mov_b32_e32 v242, v240
	v_mov_b32_e32 v243, v241
	s_nop 1
	v_permlane16_swap_b32_e32 v242, v240
	v_permlane16_swap_b32_e32 v243, v241
	v_pk_add_f32 v[240:241], v[240:241], v[242:243]
	v_mov_b32_e32 v242, v240
	v_mov_b32_e32 v243, v241
	s_nop 1
	v_permlane32_swap_b32_e32 v242, v240
	v_permlane32_swap_b32_e32 v243, v241
	v_pk_add_f32 v[244:245], v[240:241], v[242:243]
	v_cvt_pk_bf16_f32 v232, v110, v111
	v_cvt_pk_bf16_f32 v233, v112, v113
	v_cvt_pk_bf16_f32 v234, v106, v107
	v_cvt_pk_bf16_f32 v235, v108, v109
	global_store_dwordx4 v218, v[232:235], s[96:97]
	s_add_u32 s96, s96, 0x1000
	s_addc_u32 s97, s97, 0
	v_cvt_pk_bf16_f32 v236, v102, v103
	v_cvt_pk_bf16_f32 v237, v104, v105
	v_cvt_pk_bf16_f32 v238, v98, v99
	v_cvt_pk_bf16_f32 v239, v100, v101
	global_store_dwordx4 v218, v[236:239], s[96:97]
	s_add_u32 s96, s96, 0x1000
	s_addc_u32 s97, s97, 0
	s_and_saveexec_b64 vcc, s[0:1]
	global_store_dwordx2 v219, v[244:245], s[98:99]
	s_or_b64 exec, exec, vcc
	s_add_u32 s98, s98, 0x800
	s_addc_u32 s99, s99, 0
	v_mov_b32_e32 v240, v94
	v_mov_b32_e32 v241, v95
	v_pk_mul_f32 v[242:243], v[94:95], v[94:95]
	v_pk_add_f32 v[240:241], v[240:241], v[96:97]
	v_pk_fma_f32 v[242:243], v[96:97], v[96:97], v[242:243]
	v_pk_add_f32 v[240:241], v[240:241], v[90:91]
	v_pk_fma_f32 v[242:243], v[90:91], v[90:91], v[242:243]
	v_pk_add_f32 v[240:241], v[240:241], v[92:93]
	v_pk_fma_f32 v[242:243], v[92:93], v[92:93], v[242:243]
	v_pk_add_f32 v[240:241], v[240:241], v[86:87]
	v_pk_fma_f32 v[242:243], v[86:87], v[86:87], v[242:243]
	v_pk_add_f32 v[240:241], v[240:241], v[88:89]
	v_pk_fma_f32 v[242:243], v[88:89], v[88:89], v[242:243]
	v_pk_add_f32 v[240:241], v[240:241], v[82:83]
	v_pk_fma_f32 v[242:243], v[82:83], v[82:83], v[242:243]
	v_pk_add_f32 v[240:241], v[240:241], v[84:85]
	v_pk_fma_f32 v[242:243], v[84:85], v[84:85], v[242:243]
	v_add_f32_e32 v240, v240, v241
	v_add_f32_e32 v241, v242, v243
	v_mov_b32_e32 v242, v240
	v_mov_b32_e32 v243, v241
	s_nop 1
	v_permlane16_swap_b32_e32 v242, v240
	v_permlane16_swap_b32_e32 v243, v241
	v_pk_add_f32 v[240:241], v[240:241], v[242:243]
	v_mov_b32_e32 v242, v240
	v_mov_b32_e32 v243, v241
	s_nop 1
	v_permlane32_swap_b32_e32 v242, v240
	v_permlane32_swap_b32_e32 v243, v241
	v_pk_add_f32 v[244:245], v[240:241], v[242:243]
	v_cvt_pk_bf16_f32 v232, v94, v95
	v_cvt_pk_bf16_f32 v233, v96, v97
	v_cvt_pk_bf16_f32 v234, v90, v91
	v_cvt_pk_bf16_f32 v235, v92, v93
	global_store_dwordx4 v218, v[232:235], s[96:97]
; __device__ __forceinline__ unsigned cvt_pk_bf16(float lo, float hi) { unsigned r; asm volatile("v_cvt_pk_bf16_f32 %0, %1, %2" : "=v"(r) : "v"(lo), "v"(hi)); return r; }
;     __device__ __forceinline__ void operator()(const f32x4 (&acc)[2][2][4][2], const pg8::Unit& u, int wr, int wc, int fr, int fq, const LAS float* tab) const {
;     ...
;                     else if (kind == 3) {
; #pragma unroll
;                         for (int e = 0; e < 4; ++e) { s1 += v0[e] + v1[e]; s2 += v0[e] * v0[e] + v1[e] * v1[e]; }
;                     } else if (kind == 4) {
;                         v0 = v0 * f2; v1 = v1 * f2;
; #pragma unroll
;                         for (int e = 0; e < 4; ++e) s2 += v0[e] * v0[e] + v1[e] * v1[e];
;                     }
;                     u32x4 w; w.x = cvt_pk_bf16(v0[0], v0[1]); w.y = cvt_pk_bf16(v0[2], v0[3]); w.z = cvt_pk_bf16(v1[0], v1[1]); w.w = cvt_pk_bf16(v1[2], v1[3]);
;                     *(u32x4*)(rowp + bj * bjstep) = w;
;                 }
;                 if (kind == 3) {
;                     s1 += __shfl_xor(s1, 16); s1 += __shfl_xor(s1, 32); s2 += __shfl_xor(s2, 16); s2 += __shfl_xor(s2, 32);
;                     if (fq == 0) { float* p = aux + (size_t)row * 32 + ((pn - 12) * 4 + wc) * 2; p[0] = s1; p[1] = s2; }
	s_add_u32 s96, s96, 0x1000
	s_addc_u32 s97, s97, 0
	v_cvt_pk_bf16_f32 v236, v86, v87
	v_cvt_pk_bf16_f32 v237, v88, v89
	v_cvt_pk_bf16_f32 v238, v82, v83
	v_cvt_pk_bf16_f32 v239, v84, v85
	global_store_dwordx4 v218, v[236:239], s[96:97]
	s_add_u32 s96, s96, 0x1000
	s_addc_u32 s97, s97, 0
	s_and_saveexec_b64 vcc, s[0:1]
	global_store_dwordx2 v219, v[244:245], s[98:99]
	s_or_b64 exec, exec, vcc
	s_add_u32 s98, s98, 0x800
	s_addc_u32 s99, s99, 0
	v_mov_b32_e32 v240, v78
	v_mov_b32_e32 v241, v79
	v_pk_mul_f32 v[242:243], v[78:79], v[78:79]
	v_pk_add_f32 v[240:241], v[240:241], v[80:81]
	v_pk_fma_f32 v[242:243], v[80:81], v[80:81], v[242:243]
	v_pk_add_f32 v[240:241], v[240:241], v[74:75]
	v_pk_fma_f32 v[242:243], v[74:75], v[74:75], v[242:243]
	v_pk_add_f32 v[240:241], v[240:241], v[76:77]
	v_pk_fma_f32 v[242:243], v[76:77], v[76:77], v[242:243]
	v_pk_add_f32 v[240:241], v[240:241], v[70:71]
	v_pk_fma_f32 v[242:243], v[70:71], v[70:71], v[242:243]
	v_pk_add_f32 v[240:241], v[240:241], v[72:73]
	v_pk_fma_f32 v[242:243], v[72:73], v[72:73], v[242:243]
	v_pk_add_f32 v[240:241], v[240:241], v[66:67]
	v_pk_fma_f32 v[242:243], v[66:67], v[66:67], v[242:243]
	v_pk_add_f32 v[240:241], v[240:241], v[68:69]
	v_pk_fma_f32 v[242:243], v[68:69], v[68:69], v[242:243]
	v_add_f32_e32 v240, v240, v241
	v_add_f32_e32 v241, v242, v243
	v_mov_b32_e32 v242, v240
	v_mov_b32_e32 v243, v241
	s_nop 1
	v_permlane16_swap_b32_e32 v242, v240
	v_permlane16_swap_b32_e32 v243, v241
	v_pk_add_f32 v[240:241], v[240:241], v[242:243]
	v_mov_b32_e32 v242, v240
	v_mov_b32_e32 v243, v241
	s_nop 1
	v_permlane32_swap_b32_e32 v242, v240
	v_permlane32_swap_b32_e32 v243, v241
	v_pk_add_f32 v[244:245], v[240:241], v[242:243]
	v_cvt_pk_bf16_f32 v232, v78, v79
	v_cvt_pk_bf16_f32 v233, v80, v81
	v_cvt_pk_bf16_f32 v234, v74, v75
	v_cvt_pk_bf16_f32 v235, v76, v77
	global_store_dwordx4 v218, v[232:235], s[96:97]
	s_add_u32 s96, s96, 0x1000
	s_addc_u32 s97, s97, 0
	v_cvt_pk_bf16_f32 v236, v70, v71
	v_cvt_pk_bf16_f32 v237, v72, v73
	v_cvt_pk_bf16_f32 v238, v66, v67
	v_cvt_pk_bf16_f32 v239, v68, v69
	global_store_dwordx4 v218, v[236:239], s[96:97]
	s_add_u32 s96, s96, 0x1000
	s_addc_u32 s97, s97, 0
	s_add_u32 s96, s96, 0x8000
	s_addc_u32 s97, s97, 0
	s_and_saveexec_b64 vcc, s[0:1]
	global_store_dwordx2 v219, v[244:245], s[98:99]
	s_or_b64 exec, exec, vcc
	s_add_u32 s98, s98, 0x2800
	s_addc_u32 s99, s99, 0
	v_mov_b32_e32 v240, v62
	v_mov_b32_e32 v241, v63
	v_pk_mul_f32 v[242:243], v[62:63], v[62:63]
	v_pk_add_f32 v[240:241], v[240:241], v[64:65]
	v_pk_fma_f32 v[242:243], v[64:65], v[64:65], v[242:243]
	v_pk_add_f32 v[240:241], v[240:241], v[58:59]
	v_pk_fma_f32 v[242:243], v[58:59], v[58:59], v[242:243]
	v_pk_add_f32 v[240:241], v[240:241], v[60:61]
	v_pk_fma_f32 v[242:243], v[60:61], v[60:61], v[242:243]
	v_pk_add_f32 v[240:241], v[240:241], v[54:55]
	v_pk_fma_f32 v[242:243], v[54:55], v[54:55], v[242:243]
	v_pk_add_f32 v[240:241], v[240:241], v[56:57]
	v_pk_fma_f32 v[242:243], v[56:57], v[56:57], v[242:243]
	v_pk_add_f32 v[240:241], v[240:241], v[50:51]
	v_pk_fma_f32 v[242:243], v[50:51], v[50:51], v[242:243]
	v_pk_add_f32 v[240:241], v[240:241], v[52:53]
	v_pk_fma_f32 v[242:243], v[52:53], v[52:53], v[242:243]
	v_add_f32_e32 v240, v240, v241
	v_add_f32_e32 v241, v242, v243
	v_mov_b32_e32 v242, v240
	v_mov_b32_e32 v243, v241
	s_nop 1
	v_permlane16_swap_b32_e32 v242, v240
	v_permlane16_swap_b32_e32 v243, v241
	v_pk_add_f32 v[240:241], v[240:241], v[242:243]
	v_mov_b32_e32 v242, v240
	v_mov_b32_e32 v243, v241
	s_nop 1
	v_permlane32_swap_b32_e32 v242, v240
	v_permlane32_swap_b32_e32 v243, v241
	v_pk_add_f32 v[244:245], v[240:241], v[242:243]
	v_cvt_pk_bf16_f32 v232, v62, v63
	v_cvt_pk_bf16_f32 v233, v64, v65
	v_cvt_pk_bf16_f32 v234, v58, v59
	v_cvt_pk_bf16_f32 v235, v60, v61
	global_store_dwordx4 v218, v[232:235], s[96:97]
	s_add_u32 s96, s96, 0x1000
	s_addc_u32 s97, s97, 0
	v_cvt_pk_bf16_f32 v236, v54, v55
	v_cvt_pk_bf16_f32 v237, v56, v57
	v_cvt_pk_bf16_f32 v238, v50, v51
	v_cvt_pk_bf16_f32 v239, v52, v53
	global_store_dwordx4 v218, v[236:239], s[96:97]
	s_add_u32 s96, s96, 0x1000
	s_addc_u32 s97, s97, 0
	s_and_saveexec_b64 vcc, s[0:1]
	global_store_dwordx2 v219, v[244:245], s[98:99]
	s_or_b64 exec, exec, vcc
	s_add_u32 s98, s98, 0x800
	s_addc_u32 s99, s99, 0
	v_mov_b32_e32 v240, v46
	v_mov_b32_e32 v241, v47
	v_pk_mul_f32 v[242:243], v[46:47], v[46:47]
	v_pk_add_f32 v[240:241], v[240:241], v[48:49]
	v_pk_fma_f32 v[242:243], v[48:49], v[48:49], v[242:243]
	v_pk_add_f32 v[240:241], v[240:241], v[42:43]
	v_pk_fma_f32 v[242:243], v[42:43], v[42:43], v[242:243]
	v_pk_add_f32 v[240:241], v[240:241], v[44:45]
	v_pk_fma_f32 v[242:243], v[44:45], v[44:45], v[242:243]
	v_pk_add_f32 v[240:241], v[240:241], v[38:39]
	v_pk_fma_f32 v[242:243], v[38:39], v[38:39], v[242:243]
	v_pk_add_f32 v[240:241], v[240:241], v[40:41]
	v_pk_fma_f32 v[242:243], v[40:41], v[40:41], v[242:243]
	v_pk_add_f32 v[240:241], v[240:241], v[34:35]
; __device__ __forceinline__ unsigned cvt_pk_bf16(float lo, float hi) { unsigned r; asm volatile("v_cvt_pk_bf16_f32 %0, %1, %2" : "=v"(r) : "v"(lo), "v"(hi)); return r; }
;     __device__ __forceinline__ void operator()(const f32x4 (&acc)[2][2][4][2], const pg8::Unit& u, int wr, int wc, int fr, int fq, const LAS float* tab) const {
;     ...
;                     else if (kind == 3) {
; #pragma unroll
;                         for (int e = 0; e < 4; ++e) { s1 += v0[e] + v1[e]; s2 += v0[e] * v0[e] + v1[e] * v1[e]; }
;                     } else if (kind == 4) {
;                         v0 = v0 * f2; v1 = v1 * f2;
; #pragma unroll
;                         for (int e = 0; e < 4; ++e) s2 += v0[e] * v0[e] + v1[e] * v1[e];
;                     }
;                     u32x4 w; w.x = cvt_pk_bf16(v0[0], v0[1]); w.y = cvt_pk_bf16(v0[2], v0[3]); w.z = cvt_pk_bf16(v1[0], v1[1]); w.w = cvt_pk_bf16(v1[2], v1[3]);
;                     *(u32x4*)(rowp + bj * bjstep) = w;
;                 }
;                 if (kind == 3) {
;                     s1 += __shfl_xor(s1, 16); s1 += __shfl_xor(s1, 32); s2 += __shfl_xor(s2, 16); s2 += __shfl_xor(s2, 32);
;                     if (fq == 0) { float* p = aux + (size_t)row * 32 + ((pn - 12) * 4 + wc) * 2; p[0] = s1; p[1] = s2; }
	v_pk_fma_f32 v[242:243], v[34:35], v[34:35], v[242:243]
	v_pk_add_f32 v[240:241], v[240:241], v[36:37]
	v_pk_fma_f32 v[242:243], v[36:37], v[36:37], v[242:243]
	v_add_f32_e32 v240, v240, v241
	v_add_f32_e32 v241, v242, v243
	v_mov_b32_e32 v242, v240
	v_mov_b32_e32 v243, v241
	s_nop 1
	v_permlane16_swap_b32_e32 v242, v240
	v_permlane16_swap_b32_e32 v243, v241
	v_pk_add_f32 v[240:241], v[240:241], v[242:243]
	v_mov_b32_e32 v242, v240
	v_mov_b32_e32 v243, v241
	s_nop 1
	v_permlane32_swap_b32_e32 v242, v240
	v_permlane32_swap_b32_e32 v243, v241
	v_pk_add_f32 v[244:245], v[240:241], v[242:243]
	v_cvt_pk_bf16_f32 v232, v46, v47
	v_cvt_pk_bf16_f32 v233, v48, v49
	v_cvt_pk_bf16_f32 v234, v42, v43
	v_cvt_pk_bf16_f32 v235, v44, v45
	global_store_dwordx4 v218, v[232:235], s[96:97]
	s_add_u32 s96, s96, 0x1000
	s_addc_u32 s97, s97, 0
	v_cvt_pk_bf16_f32 v236, v38, v39
	v_cvt_pk_bf16_f32 v237, v40, v41
	v_cvt_pk_bf16_f32 v238, v34, v35
	v_cvt_pk_bf16_f32 v239, v36, v37
	global_store_dwordx4 v218, v[236:239], s[96:97]
	s_add_u32 s96, s96, 0x1000
	s_addc_u32 s97, s97, 0
	s_and_saveexec_b64 vcc, s[0:1]
	global_store_dwordx2 v219, v[244:245], s[98:99]
	s_or_b64 exec, exec, vcc
	s_add_u32 s98, s98, 0x800
	s_addc_u32 s99, s99, 0
	v_mov_b32_e32 v240, v30
	v_mov_b32_e32 v241, v31
	v_pk_mul_f32 v[242:243], v[30:31], v[30:31]
	v_pk_add_f32 v[240:241], v[240:241], v[32:33]
	v_pk_fma_f32 v[242:243], v[32:33], v[32:33], v[242:243]
	v_pk_add_f32 v[240:241], v[240:241], v[26:27]
	v_pk_fma_f32 v[242:243], v[26:27], v[26:27], v[242:243]
	v_pk_add_f32 v[240:241], v[240:241], v[28:29]
	v_pk_fma_f32 v[242:243], v[28:29], v[28:29], v[242:243]
	v_pk_add_f32 v[240:241], v[240:241], v[22:23]
	v_pk_fma_f32 v[242:243], v[22:23], v[22:23], v[242:243]
	v_pk_add_f32 v[240:241], v[240:241], v[24:25]
	v_pk_fma_f32 v[242:243], v[24:25], v[24:25], v[242:243]
	v_pk_add_f32 v[240:241], v[240:241], v[18:19]
	v_pk_fma_f32 v[242:243], v[18:19], v[18:19], v[242:243]
	v_pk_add_f32 v[240:241], v[240:241], v[20:21]
	v_pk_fma_f32 v[242:243], v[20:21], v[20:21], v[242:243]
	v_add_f32_e32 v240, v240, v241
	v_add_f32_e32 v241, v242, v243
	v_mov_b32_e32 v242, v240
	v_mov_b32_e32 v243, v241
	s_nop 1
	v_permlane16_swap_b32_e32 v242, v240
	v_permlane16_swap_b32_e32 v243, v241
	v_pk_add_f32 v[240:241], v[240:241], v[242:243]
	v_mov_b32_e32 v242, v240
	v_mov_b32_e32 v243, v241
	s_nop 1
	v_permlane32_swap_b32_e32 v242, v240
	v_permlane32_swap_b32_e32 v243, v241
	v_pk_add_f32 v[244:245], v[240:241], v[242:243]
	v_cvt_pk_bf16_f32 v232, v30, v31
	v_cvt_pk_bf16_f32 v233, v32, v33
	v_cvt_pk_bf16_f32 v234, v26, v27
	v_cvt_pk_bf16_f32 v235, v28, v29
	global_store_dwordx4 v218, v[232:235], s[96:97]
	s_add_u32 s96, s96, 0x1000
	s_addc_u32 s97, s97, 0
	v_cvt_pk_bf16_f32 v236, v22, v23
	v_cvt_pk_bf16_f32 v237, v24, v25
	v_cvt_pk_bf16_f32 v238, v18, v19
	v_cvt_pk_bf16_f32 v239, v20, v21
	global_store_dwordx4 v218, v[236:239], s[96:97]
	s_add_u32 s96, s96, 0x1000
	s_addc_u32 s97, s97, 0
	s_and_saveexec_b64 vcc, s[0:1]
	global_store_dwordx2 v219, v[244:245], s[98:99]
	s_or_b64 exec, exec, vcc
	s_add_u32 s98, s98, 0x800
	s_addc_u32 s99, s99, 0
	v_mov_b32_e32 v240, v14
	v_mov_b32_e32 v241, v15
	v_pk_mul_f32 v[242:243], v[14:15], v[14:15]
	v_pk_add_f32 v[240:241], v[240:241], v[16:17]
	v_pk_fma_f32 v[242:243], v[16:17], v[16:17], v[242:243]
	v_pk_add_f32 v[240:241], v[240:241], v[10:11]
	v_pk_fma_f32 v[242:243], v[10:11], v[10:11], v[242:243]
	v_pk_add_f32 v[240:241], v[240:241], v[12:13]
	v_pk_fma_f32 v[242:243], v[12:13], v[12:13], v[242:243]
	v_pk_add_f32 v[240:241], v[240:241], v[6:7]
	v_pk_fma_f32 v[242:243], v[6:7], v[6:7], v[242:243]
	v_pk_add_f32 v[240:241], v[240:241], v[8:9]
	v_pk_fma_f32 v[242:243], v[8:9], v[8:9], v[242:243]
	v_pk_add_f32 v[240:241], v[240:241], v[2:3]
	v_pk_fma_f32 v[242:243], v[2:3], v[2:3], v[242:243]
	v_pk_add_f32 v[240:241], v[240:241], v[4:5]
	v_pk_fma_f32 v[242:243], v[4:5], v[4:5], v[242:243]
	v_add_f32_e32 v240, v240, v241
	v_add_f32_e32 v241, v242, v243
	v_mov_b32_e32 v242, v240
	v_mov_b32_e32 v243, v241
	s_nop 1
	v_permlane16_swap_b32_e32 v242, v240
	v_permlane16_swap_b32_e32 v243, v241
	v_pk_add_f32 v[240:241], v[240:241], v[242:243]
	v_mov_b32_e32 v242, v240
	v_mov_b32_e32 v243, v241
	s_nop 1
	v_permlane32_swap_b32_e32 v242, v240
	v_permlane32_swap_b32_e32 v243, v241
	v_pk_add_f32 v[244:245], v[240:241], v[242:243]
	v_cvt_pk_bf16_f32 v232, v14, v15
	v_cvt_pk_bf16_f32 v233, v16, v17
	v_cvt_pk_bf16_f32 v234, v10, v11
	v_cvt_pk_bf16_f32 v235, v12, v13
	global_store_dwordx4 v218, v[232:235], s[96:97]
	s_add_u32 s96, s96, 0x1000
	s_addc_u32 s97, s97, 0
	v_cvt_pk_bf16_f32 v236, v6, v7
	v_cvt_pk_bf16_f32 v237, v8, v9
	v_cvt_pk_bf16_f32 v238, v2, v3
	v_cvt_pk_bf16_f32 v239, v4, v5
	global_store_dwordx4 v218, v[236:239], s[96:97]
	s_add_u32 s96, s96, 0x1000
	s_addc_u32 s97, s97, 0
	s_and_saveexec_b64 vcc, s[0:1]
	global_store_dwordx2 v219, v[244:245], s[98:99]
	s_or_b64 exec, exec, vcc
	s_add_u32 s98, s98, 0x800
	s_addc_u32 s99, s99, 0
	s_branch .LBB0_391
